# wave 0 runs the phase-2 inversion at raised priority (s_setprio 3 .. 0): it is the stage pole and shares its SIMD with wave 4
# baseline (speedup 1.0000x reference)
.LBB0_664:
	s_or_saveexec_b64 s[12:13], s[16:17]
	v_and_b32_e32 v95, 31, v94
	s_xor_b64 exec, exec, s[12:13]
	s_cbranch_execz .LBB0_666
	s_setprio 3
	v_and_b32_e32 v0, 32, v94
	v_lshlrev_b32_e32 v1, 8, v0
	v_lshlrev_b32_e32 v2, 2, v0
	v_add3_u32 v11, s91, v1, v2
	v_mov_b32_e32 v241, 0
	v_mov_b32_e32 v249, 0
	ds_read_b128 v[204:207], v11 offset:256
	v_cmp_eq_u32_e32 vcc, 0, v95
	v_lshl_add_u32 v244, v95, 1, s95
	v_mad_u32_u24 v0, v0, s93, v244
	v_cndmask_b32_e64 v12, 0, 1.0, vcc
	v_cmp_eq_u32_e32 vcc, 1, v95
	s_nop 1
	v_cndmask_b32_e64 v248, 0, 1.0, vcc
	v_cmp_eq_u32_e32 vcc, 2, v95
	ds_read_b128 v[172:175], v11 offset:512
	s_waitcnt lgkmcnt(1)
	v_cndmask_b32_e64 v240, 0, 1.0, vcc
	v_fma_f32 v13, -v204, v12, v248
	v_cmp_eq_u32_e32 vcc, 3, v95
	ds_read_b128 v[204:207], v11 offset:768
	s_waitcnt lgkmcnt(1)
	v_pk_fma_f32 v[242:243], v[172:173], v[12:13], v[240:241] neg_lo:[1,0,0] neg_hi:[1,0,0]
	v_cndmask_b32_e64 v248, 0, 1.0, vcc
	v_add_f32_e32 v14, v242, v243
	v_cmp_eq_u32_e32 vcc, 4, v95
	ds_read_b128 v[172:175], v11 offset:1024
	s_waitcnt lgkmcnt(1)
	v_pk_fma_f32 v[242:243], v[204:205], v[12:13], v[248:249] neg_lo:[1,0,0] neg_hi:[1,0,0]
	v_cndmask_b32_e64 v240, 0, 1.0, vcc
	v_fma_f32 v242, -v206, v14, v242
	v_add_f32_e32 v15, v242, v243
	v_cmp_eq_u32_e32 vcc, 5, v95
	ds_read_b128 v[204:207], v11 offset:1280
	ds_read_b128 v[208:211], v11 offset:1296
	s_waitcnt lgkmcnt(2)
	v_pk_fma_f32 v[242:243], v[172:173], v[12:13], v[240:241] neg_lo:[1,0,0] neg_hi:[1,0,0]
	v_pk_fma_f32 v[242:243], v[174:175], v[14:15], v[242:243] neg_lo:[1,0,0] neg_hi:[1,0,0]
	v_cndmask_b32_e64 v248, 0, 1.0, vcc
	v_add_f32_e32 v16, v242, v243
	v_cmp_eq_u32_e32 vcc, 6, v95
	ds_read_b128 v[172:175], v11 offset:1536
	ds_read_b128 v[176:179], v11 offset:1552
	s_waitcnt lgkmcnt(2)
	v_pk_fma_f32 v[242:243], v[204:205], v[12:13], v[248:249] neg_lo:[1,0,0] neg_hi:[1,0,0]
	v_pk_fma_f32 v[242:243], v[206:207], v[14:15], v[242:243] neg_lo:[1,0,0] neg_hi:[1,0,0]
	v_cndmask_b32_e64 v240, 0, 1.0, vcc
	v_fma_f32 v242, -v208, v16, v242
	v_add_f32_e32 v17, v242, v243
	v_cmp_eq_u32_e32 vcc, 7, v95
	ds_read_b128 v[204:207], v11 offset:1792
	ds_read_b128 v[208:211], v11 offset:1808
	s_waitcnt lgkmcnt(2)
	v_pk_fma_f32 v[242:243], v[172:173], v[12:13], v[240:241] neg_lo:[1,0,0] neg_hi:[1,0,0]
	v_pk_fma_f32 v[242:243], v[174:175], v[14:15], v[242:243] neg_lo:[1,0,0] neg_hi:[1,0,0]
	v_pk_fma_f32 v[242:243], v[176:177], v[16:17], v[242:243] neg_lo:[1,0,0] neg_hi:[1,0,0]
	v_cndmask_b32_e64 v248, 0, 1.0, vcc
	v_add_f32_e32 v18, v242, v243
	v_cmp_eq_u32_e32 vcc, 8, v95
	ds_read_b128 v[172:175], v11 offset:2048
	ds_read_b128 v[176:179], v11 offset:2064
	s_waitcnt lgkmcnt(2)
	v_pk_fma_f32 v[242:243], v[204:205], v[12:13], v[248:249] neg_lo:[1,0,0] neg_hi:[1,0,0]
	v_pk_fma_f32 v[242:243], v[206:207], v[14:15], v[242:243] neg_lo:[1,0,0] neg_hi:[1,0,0]
	v_pk_fma_f32 v[242:243], v[208:209], v[16:17], v[242:243] neg_lo:[1,0,0] neg_hi:[1,0,0]
	v_cndmask_b32_e64 v240, 0, 1.0, vcc
	v_fma_f32 v242, -v210, v18, v242
	v_add_f32_e32 v19, v242, v243
	v_cmp_eq_u32_e32 vcc, 9, v95
	ds_read_b128 v[204:207], v11 offset:2304
	ds_read_b128 v[208:211], v11 offset:2320
	ds_read_b128 v[212:215], v11 offset:2336
	s_waitcnt lgkmcnt(3)
	v_pk_fma_f32 v[242:243], v[172:173], v[12:13], v[240:241] neg_lo:[1,0,0] neg_hi:[1,0,0]
	v_pk_fma_f32 v[242:243], v[174:175], v[14:15], v[242:243] neg_lo:[1,0,0] neg_hi:[1,0,0]
	v_pk_fma_f32 v[242:243], v[176:177], v[16:17], v[242:243] neg_lo:[1,0,0] neg_hi:[1,0,0]
	v_pk_fma_f32 v[242:243], v[178:179], v[18:19], v[242:243] neg_lo:[1,0,0] neg_hi:[1,0,0]
	v_cndmask_b32_e64 v248, 0, 1.0, vcc
	v_add_f32_e32 v20, v242, v243
	v_cmp_eq_u32_e32 vcc, 10, v95
	ds_read_b128 v[172:175], v11 offset:2560
	ds_read_b128 v[176:179], v11 offset:2576
	ds_read_b128 v[180:183], v11 offset:2592
	s_waitcnt lgkmcnt(3)
	v_pk_fma_f32 v[242:243], v[204:205], v[12:13], v[248:249] neg_lo:[1,0,0] neg_hi:[1,0,0]
	v_pk_fma_f32 v[242:243], v[206:207], v[14:15], v[242:243] neg_lo:[1,0,0] neg_hi:[1,0,0]
	v_pk_fma_f32 v[242:243], v[208:209], v[16:17], v[242:243] neg_lo:[1,0,0] neg_hi:[1,0,0]
	v_pk_fma_f32 v[242:243], v[210:211], v[18:19], v[242:243] neg_lo:[1,0,0] neg_hi:[1,0,0]
	v_cndmask_b32_e64 v240, 0, 1.0, vcc
	v_fma_f32 v242, -v212, v20, v242
	v_add_f32_e32 v21, v242, v243
	v_cmp_eq_u32_e32 vcc, 11, v95
	ds_read_b128 v[204:207], v11 offset:2816
	ds_read_b128 v[208:211], v11 offset:2832
	ds_read_b128 v[212:215], v11 offset:2848
	s_waitcnt lgkmcnt(3)
	v_pk_fma_f32 v[242:243], v[172:173], v[12:13], v[240:241] neg_lo:[1,0,0] neg_hi:[1,0,0]
	v_pk_fma_f32 v[242:243], v[174:175], v[14:15], v[242:243] neg_lo:[1,0,0] neg_hi:[1,0,0]
	v_pk_fma_f32 v[242:243], v[176:177], v[16:17], v[242:243] neg_lo:[1,0,0] neg_hi:[1,0,0]
	v_pk_fma_f32 v[242:243], v[178:179], v[18:19], v[242:243] neg_lo:[1,0,0] neg_hi:[1,0,0]
	v_pk_fma_f32 v[242:243], v[180:181], v[20:21], v[242:243] neg_lo:[1,0,0] neg_hi:[1,0,0]
	v_cndmask_b32_e64 v248, 0, 1.0, vcc
	v_add_f32_e32 v22, v242, v243
	v_cmp_eq_u32_e32 vcc, 12, v95
	ds_read_b128 v[172:175], v11 offset:3072
	ds_read_b128 v[176:179], v11 offset:3088
	ds_read_b128 v[180:183], v11 offset:3104
	s_waitcnt lgkmcnt(3)
	v_pk_fma_f32 v[242:243], v[204:205], v[12:13], v[248:249] neg_lo:[1,0,0] neg_hi:[1,0,0]
	v_pk_fma_f32 v[242:243], v[206:207], v[14:15], v[242:243] neg_lo:[1,0,0] neg_hi:[1,0,0]
	v_pk_fma_f32 v[242:243], v[208:209], v[16:17], v[242:243] neg_lo:[1,0,0] neg_hi:[1,0,0]
	v_pk_fma_f32 v[242:243], v[210:211], v[18:19], v[242:243] neg_lo:[1,0,0] neg_hi:[1,0,0]
	v_pk_fma_f32 v[242:243], v[212:213], v[20:21], v[242:243] neg_lo:[1,0,0] neg_hi:[1,0,0]
	v_cndmask_b32_e64 v240, 0, 1.0, vcc
	v_fma_f32 v242, -v214, v22, v242
	v_add_f32_e32 v23, v242, v243
	v_cmp_eq_u32_e32 vcc, 13, v95
	ds_read_b128 v[204:207], v11 offset:3328
	ds_read_b128 v[208:211], v11 offset:3344
	ds_read_b128 v[212:215], v11 offset:3360
	ds_read_b128 v[216:219], v11 offset:3376
	s_waitcnt lgkmcnt(4)
	v_pk_fma_f32 v[242:243], v[172:173], v[12:13], v[240:241] neg_lo:[1,0,0] neg_hi:[1,0,0]
	v_pk_fma_f32 v[242:243], v[174:175], v[14:15], v[242:243] neg_lo:[1,0,0] neg_hi:[1,0,0]
	v_pk_fma_f32 v[242:243], v[176:177], v[16:17], v[242:243] neg_lo:[1,0,0] neg_hi:[1,0,0]
	v_pk_fma_f32 v[242:243], v[178:179], v[18:19], v[242:243] neg_lo:[1,0,0] neg_hi:[1,0,0]
	v_pk_fma_f32 v[242:243], v[180:181], v[20:21], v[242:243] neg_lo:[1,0,0] neg_hi:[1,0,0]
	v_pk_fma_f32 v[242:243], v[182:183], v[22:23], v[242:243] neg_lo:[1,0,0] neg_hi:[1,0,0]
	v_cndmask_b32_e64 v248, 0, 1.0, vcc
	v_add_f32_e32 v24, v242, v243
	v_cmp_eq_u32_e32 vcc, 14, v95
	ds_read_b128 v[172:175], v11 offset:3584
	ds_read_b128 v[176:179], v11 offset:3600
	ds_read_b128 v[180:183], v11 offset:3616
	ds_read_b128 v[184:187], v11 offset:3632
	s_waitcnt lgkmcnt(4)
	v_pk_fma_f32 v[242:243], v[204:205], v[12:13], v[248:249] neg_lo:[1,0,0] neg_hi:[1,0,0]
	v_pk_fma_f32 v[242:243], v[206:207], v[14:15], v[242:243] neg_lo:[1,0,0] neg_hi:[1,0,0]
	v_pk_fma_f32 v[242:243], v[208:209], v[16:17], v[242:243] neg_lo:[1,0,0] neg_hi:[1,0,0]
	v_pk_fma_f32 v[242:243], v[210:211], v[18:19], v[242:243] neg_lo:[1,0,0] neg_hi:[1,0,0]
	v_pk_fma_f32 v[242:243], v[212:213], v[20:21], v[242:243] neg_lo:[1,0,0] neg_hi:[1,0,0]
	v_pk_fma_f32 v[242:243], v[214:215], v[22:23], v[242:243] neg_lo:[1,0,0] neg_hi:[1,0,0]
	v_cndmask_b32_e64 v240, 0, 1.0, vcc
	v_fma_f32 v242, -v216, v24, v242
	v_add_f32_e32 v25, v242, v243
	v_cmp_eq_u32_e32 vcc, 15, v95
	ds_read_b128 v[204:207], v11 offset:3840
	ds_read_b128 v[208:211], v11 offset:3856
	ds_read_b128 v[212:215], v11 offset:3872
	ds_read_b128 v[216:219], v11 offset:3888
	s_waitcnt lgkmcnt(4)
	v_pk_fma_f32 v[242:243], v[172:173], v[12:13], v[240:241] neg_lo:[1,0,0] neg_hi:[1,0,0]
	v_pk_fma_f32 v[242:243], v[174:175], v[14:15], v[242:243] neg_lo:[1,0,0] neg_hi:[1,0,0]
	v_pk_fma_f32 v[242:243], v[176:177], v[16:17], v[242:243] neg_lo:[1,0,0] neg_hi:[1,0,0]
	v_pk_fma_f32 v[242:243], v[178:179], v[18:19], v[242:243] neg_lo:[1,0,0] neg_hi:[1,0,0]
	v_pk_fma_f32 v[242:243], v[180:181], v[20:21], v[242:243] neg_lo:[1,0,0] neg_hi:[1,0,0]
	v_pk_fma_f32 v[242:243], v[182:183], v[22:23], v[242:243] neg_lo:[1,0,0] neg_hi:[1,0,0]
	v_pk_fma_f32 v[242:243], v[184:185], v[24:25], v[242:243] neg_lo:[1,0,0] neg_hi:[1,0,0]
	v_cndmask_b32_e64 v248, 0, 1.0, vcc
	v_add_f32_e32 v26, v242, v243
	v_cmp_eq_u32_e32 vcc, 16, v95
	ds_read_b128 v[172:175], v11 offset:4096
	ds_read_b128 v[176:179], v11 offset:4112
	ds_read_b128 v[180:183], v11 offset:4128
	ds_read_b128 v[184:187], v11 offset:4144
	s_waitcnt lgkmcnt(4)
	v_pk_fma_f32 v[242:243], v[204:205], v[12:13], v[248:249] neg_lo:[1,0,0] neg_hi:[1,0,0]
	v_pk_fma_f32 v[242:243], v[206:207], v[14:15], v[242:243] neg_lo:[1,0,0] neg_hi:[1,0,0]
	v_pk_fma_f32 v[242:243], v[208:209], v[16:17], v[242:243] neg_lo:[1,0,0] neg_hi:[1,0,0]
	v_pk_fma_f32 v[242:243], v[210:211], v[18:19], v[242:243] neg_lo:[1,0,0] neg_hi:[1,0,0]
	v_pk_fma_f32 v[242:243], v[212:213], v[20:21], v[242:243] neg_lo:[1,0,0] neg_hi:[1,0,0]
	v_pk_fma_f32 v[242:243], v[214:215], v[22:23], v[242:243] neg_lo:[1,0,0] neg_hi:[1,0,0]
	v_pk_fma_f32 v[242:243], v[216:217], v[24:25], v[242:243] neg_lo:[1,0,0] neg_hi:[1,0,0]
	v_cndmask_b32_e64 v240, 0, 1.0, vcc
	v_fma_f32 v242, -v218, v26, v242
	v_add_f32_e32 v27, v242, v243
	v_cmp_eq_u32_e32 vcc, 17, v95
	ds_read_b128 v[204:207], v11 offset:4352
	ds_read_b128 v[208:211], v11 offset:4368
	ds_read_b128 v[212:215], v11 offset:4384
	ds_read_b128 v[216:219], v11 offset:4400
	ds_read_b128 v[220:223], v11 offset:4416
	s_waitcnt lgkmcnt(5)
	v_pk_fma_f32 v[242:243], v[172:173], v[12:13], v[240:241] neg_lo:[1,0,0] neg_hi:[1,0,0]
	v_pk_fma_f32 v[242:243], v[174:175], v[14:15], v[242:243] neg_lo:[1,0,0] neg_hi:[1,0,0]
	v_pk_fma_f32 v[242:243], v[176:177], v[16:17], v[242:243] neg_lo:[1,0,0] neg_hi:[1,0,0]
	v_pk_fma_f32 v[242:243], v[178:179], v[18:19], v[242:243] neg_lo:[1,0,0] neg_hi:[1,0,0]
	v_pk_fma_f32 v[242:243], v[180:181], v[20:21], v[242:243] neg_lo:[1,0,0] neg_hi:[1,0,0]
	v_pk_fma_f32 v[242:243], v[182:183], v[22:23], v[242:243] neg_lo:[1,0,0] neg_hi:[1,0,0]
	v_pk_fma_f32 v[242:243], v[184:185], v[24:25], v[242:243] neg_lo:[1,0,0] neg_hi:[1,0,0]
	v_pk_fma_f32 v[242:243], v[186:187], v[26:27], v[242:243] neg_lo:[1,0,0] neg_hi:[1,0,0]
	v_cndmask_b32_e64 v248, 0, 1.0, vcc
	v_add_f32_e32 v28, v242, v243
	v_cmp_eq_u32_e32 vcc, 18, v95
	ds_read_b128 v[172:175], v11 offset:4608
	ds_read_b128 v[176:179], v11 offset:4624
	ds_read_b128 v[180:183], v11 offset:4640
	ds_read_b128 v[184:187], v11 offset:4656
	ds_read_b128 v[188:191], v11 offset:4672
	s_waitcnt lgkmcnt(5)
	v_pk_fma_f32 v[242:243], v[204:205], v[12:13], v[248:249] neg_lo:[1,0,0] neg_hi:[1,0,0]
	v_pk_fma_f32 v[242:243], v[206:207], v[14:15], v[242:243] neg_lo:[1,0,0] neg_hi:[1,0,0]
	v_pk_fma_f32 v[242:243], v[208:209], v[16:17], v[242:243] neg_lo:[1,0,0] neg_hi:[1,0,0]
	v_pk_fma_f32 v[242:243], v[210:211], v[18:19], v[242:243] neg_lo:[1,0,0] neg_hi:[1,0,0]
	v_pk_fma_f32 v[242:243], v[212:213], v[20:21], v[242:243] neg_lo:[1,0,0] neg_hi:[1,0,0]
	v_pk_fma_f32 v[242:243], v[214:215], v[22:23], v[242:243] neg_lo:[1,0,0] neg_hi:[1,0,0]
	v_pk_fma_f32 v[242:243], v[216:217], v[24:25], v[242:243] neg_lo:[1,0,0] neg_hi:[1,0,0]
	v_pk_fma_f32 v[242:243], v[218:219], v[26:27], v[242:243] neg_lo:[1,0,0] neg_hi:[1,0,0]
	v_cndmask_b32_e64 v240, 0, 1.0, vcc
	v_fma_f32 v242, -v220, v28, v242
	v_add_f32_e32 v29, v242, v243
	v_cmp_eq_u32_e32 vcc, 19, v95
	ds_read_b128 v[204:207], v11 offset:4864
	ds_read_b128 v[208:211], v11 offset:4880
	ds_read_b128 v[212:215], v11 offset:4896
	ds_read_b128 v[216:219], v11 offset:4912
	ds_read_b128 v[220:223], v11 offset:4928
	s_waitcnt lgkmcnt(5)
	v_pk_fma_f32 v[242:243], v[172:173], v[12:13], v[240:241] neg_lo:[1,0,0] neg_hi:[1,0,0]
	v_pk_fma_f32 v[242:243], v[174:175], v[14:15], v[242:243] neg_lo:[1,0,0] neg_hi:[1,0,0]
	v_pk_fma_f32 v[242:243], v[176:177], v[16:17], v[242:243] neg_lo:[1,0,0] neg_hi:[1,0,0]
	v_pk_fma_f32 v[242:243], v[178:179], v[18:19], v[242:243] neg_lo:[1,0,0] neg_hi:[1,0,0]
	v_pk_fma_f32 v[242:243], v[180:181], v[20:21], v[242:243] neg_lo:[1,0,0] neg_hi:[1,0,0]
	v_pk_fma_f32 v[242:243], v[182:183], v[22:23], v[242:243] neg_lo:[1,0,0] neg_hi:[1,0,0]
	v_pk_fma_f32 v[242:243], v[184:185], v[24:25], v[242:243] neg_lo:[1,0,0] neg_hi:[1,0,0]
	v_pk_fma_f32 v[242:243], v[186:187], v[26:27], v[242:243] neg_lo:[1,0,0] neg_hi:[1,0,0]
	v_pk_fma_f32 v[242:243], v[188:189], v[28:29], v[242:243] neg_lo:[1,0,0] neg_hi:[1,0,0]
	v_cndmask_b32_e64 v248, 0, 1.0, vcc
	v_add_f32_e32 v30, v242, v243
	v_cmp_eq_u32_e32 vcc, 20, v95
	ds_read_b128 v[172:175], v11 offset:5120
	ds_read_b128 v[176:179], v11 offset:5136
	ds_read_b128 v[180:183], v11 offset:5152
	ds_read_b128 v[184:187], v11 offset:5168
	ds_read_b128 v[188:191], v11 offset:5184
	s_waitcnt lgkmcnt(5)
	v_pk_fma_f32 v[242:243], v[204:205], v[12:13], v[248:249] neg_lo:[1,0,0] neg_hi:[1,0,0]
	v_pk_fma_f32 v[242:243], v[206:207], v[14:15], v[242:243] neg_lo:[1,0,0] neg_hi:[1,0,0]
	v_pk_fma_f32 v[242:243], v[208:209], v[16:17], v[242:243] neg_lo:[1,0,0] neg_hi:[1,0,0]
	v_pk_fma_f32 v[242:243], v[210:211], v[18:19], v[242:243] neg_lo:[1,0,0] neg_hi:[1,0,0]
	v_pk_fma_f32 v[242:243], v[212:213], v[20:21], v[242:243] neg_lo:[1,0,0] neg_hi:[1,0,0]
	v_pk_fma_f32 v[242:243], v[214:215], v[22:23], v[242:243] neg_lo:[1,0,0] neg_hi:[1,0,0]
	v_pk_fma_f32 v[242:243], v[216:217], v[24:25], v[242:243] neg_lo:[1,0,0] neg_hi:[1,0,0]
	v_pk_fma_f32 v[242:243], v[218:219], v[26:27], v[242:243] neg_lo:[1,0,0] neg_hi:[1,0,0]
	v_pk_fma_f32 v[242:243], v[220:221], v[28:29], v[242:243] neg_lo:[1,0,0] neg_hi:[1,0,0]
	v_cndmask_b32_e64 v240, 0, 1.0, vcc
	v_fma_f32 v242, -v222, v30, v242
	v_add_f32_e32 v31, v242, v243
	v_cmp_eq_u32_e32 vcc, 21, v95
	ds_read_b128 v[204:207], v11 offset:5376
	ds_read_b128 v[208:211], v11 offset:5392
	ds_read_b128 v[212:215], v11 offset:5408
	ds_read_b128 v[216:219], v11 offset:5424
	ds_read_b128 v[220:223], v11 offset:5440
	ds_read_b128 v[224:227], v11 offset:5456
	s_waitcnt lgkmcnt(6)
	v_pk_fma_f32 v[242:243], v[172:173], v[12:13], v[240:241] neg_lo:[1,0,0] neg_hi:[1,0,0]
	v_pk_fma_f32 v[242:243], v[174:175], v[14:15], v[242:243] neg_lo:[1,0,0] neg_hi:[1,0,0]
	v_pk_fma_f32 v[242:243], v[176:177], v[16:17], v[242:243] neg_lo:[1,0,0] neg_hi:[1,0,0]
	v_pk_fma_f32 v[242:243], v[178:179], v[18:19], v[242:243] neg_lo:[1,0,0] neg_hi:[1,0,0]
	v_pk_fma_f32 v[242:243], v[180:181], v[20:21], v[242:243] neg_lo:[1,0,0] neg_hi:[1,0,0]
	v_pk_fma_f32 v[242:243], v[182:183], v[22:23], v[242:243] neg_lo:[1,0,0] neg_hi:[1,0,0]
	v_pk_fma_f32 v[242:243], v[184:185], v[24:25], v[242:243] neg_lo:[1,0,0] neg_hi:[1,0,0]
	v_pk_fma_f32 v[242:243], v[186:187], v[26:27], v[242:243] neg_lo:[1,0,0] neg_hi:[1,0,0]
	v_pk_fma_f32 v[242:243], v[188:189], v[28:29], v[242:243] neg_lo:[1,0,0] neg_hi:[1,0,0]
	v_pk_fma_f32 v[242:243], v[190:191], v[30:31], v[242:243] neg_lo:[1,0,0] neg_hi:[1,0,0]
	v_cndmask_b32_e64 v248, 0, 1.0, vcc
	v_add_f32_e32 v32, v242, v243
	v_cmp_eq_u32_e32 vcc, 22, v95
	ds_read_b128 v[172:175], v11 offset:5632
	ds_read_b128 v[176:179], v11 offset:5648
	ds_read_b128 v[180:183], v11 offset:5664
	ds_read_b128 v[184:187], v11 offset:5680
	ds_read_b128 v[188:191], v11 offset:5696
	ds_read_b128 v[192:195], v11 offset:5712
	s_waitcnt lgkmcnt(6)
	v_pk_fma_f32 v[242:243], v[204:205], v[12:13], v[248:249] neg_lo:[1,0,0] neg_hi:[1,0,0]
	v_pk_fma_f32 v[242:243], v[206:207], v[14:15], v[242:243] neg_lo:[1,0,0] neg_hi:[1,0,0]
	v_pk_fma_f32 v[242:243], v[208:209], v[16:17], v[242:243] neg_lo:[1,0,0] neg_hi:[1,0,0]
	v_pk_fma_f32 v[242:243], v[210:211], v[18:19], v[242:243] neg_lo:[1,0,0] neg_hi:[1,0,0]
	v_pk_fma_f32 v[242:243], v[212:213], v[20:21], v[242:243] neg_lo:[1,0,0] neg_hi:[1,0,0]
	v_pk_fma_f32 v[242:243], v[214:215], v[22:23], v[242:243] neg_lo:[1,0,0] neg_hi:[1,0,0]
	v_pk_fma_f32 v[242:243], v[216:217], v[24:25], v[242:243] neg_lo:[1,0,0] neg_hi:[1,0,0]
	v_pk_fma_f32 v[242:243], v[218:219], v[26:27], v[242:243] neg_lo:[1,0,0] neg_hi:[1,0,0]
	v_pk_fma_f32 v[242:243], v[220:221], v[28:29], v[242:243] neg_lo:[1,0,0] neg_hi:[1,0,0]
	v_pk_fma_f32 v[242:243], v[222:223], v[30:31], v[242:243] neg_lo:[1,0,0] neg_hi:[1,0,0]
	v_cndmask_b32_e64 v240, 0, 1.0, vcc
	v_fma_f32 v242, -v224, v32, v242
	v_add_f32_e32 v33, v242, v243
	v_cmp_eq_u32_e32 vcc, 23, v95
	ds_read_b128 v[204:207], v11 offset:5888
	ds_read_b128 v[208:211], v11 offset:5904
	ds_read_b128 v[212:215], v11 offset:5920
	ds_read_b128 v[216:219], v11 offset:5936
	ds_read_b128 v[220:223], v11 offset:5952
	ds_read_b128 v[224:227], v11 offset:5968
	s_waitcnt lgkmcnt(6)
	v_pk_fma_f32 v[242:243], v[172:173], v[12:13], v[240:241] neg_lo:[1,0,0] neg_hi:[1,0,0]
	v_pk_fma_f32 v[242:243], v[174:175], v[14:15], v[242:243] neg_lo:[1,0,0] neg_hi:[1,0,0]
	v_pk_fma_f32 v[242:243], v[176:177], v[16:17], v[242:243] neg_lo:[1,0,0] neg_hi:[1,0,0]
	v_pk_fma_f32 v[242:243], v[178:179], v[18:19], v[242:243] neg_lo:[1,0,0] neg_hi:[1,0,0]
	v_pk_fma_f32 v[242:243], v[180:181], v[20:21], v[242:243] neg_lo:[1,0,0] neg_hi:[1,0,0]
	v_pk_fma_f32 v[242:243], v[182:183], v[22:23], v[242:243] neg_lo:[1,0,0] neg_hi:[1,0,0]
	v_pk_fma_f32 v[242:243], v[184:185], v[24:25], v[242:243] neg_lo:[1,0,0] neg_hi:[1,0,0]
	v_pk_fma_f32 v[242:243], v[186:187], v[26:27], v[242:243] neg_lo:[1,0,0] neg_hi:[1,0,0]
	v_pk_fma_f32 v[242:243], v[188:189], v[28:29], v[242:243] neg_lo:[1,0,0] neg_hi:[1,0,0]
	v_pk_fma_f32 v[242:243], v[190:191], v[30:31], v[242:243] neg_lo:[1,0,0] neg_hi:[1,0,0]
	v_pk_fma_f32 v[242:243], v[192:193], v[32:33], v[242:243] neg_lo:[1,0,0] neg_hi:[1,0,0]
	v_cndmask_b32_e64 v248, 0, 1.0, vcc
	v_add_f32_e32 v34, v242, v243
	v_cmp_eq_u32_e32 vcc, 24, v95
	ds_read_b128 v[172:175], v11 offset:6144
	ds_read_b128 v[176:179], v11 offset:6160
	ds_read_b128 v[180:183], v11 offset:6176
	ds_read_b128 v[184:187], v11 offset:6192
	ds_read_b128 v[188:191], v11 offset:6208
	ds_read_b128 v[192:195], v11 offset:6224
	s_waitcnt lgkmcnt(6)
	v_pk_fma_f32 v[242:243], v[204:205], v[12:13], v[248:249] neg_lo:[1,0,0] neg_hi:[1,0,0]
	v_pk_fma_f32 v[242:243], v[206:207], v[14:15], v[242:243] neg_lo:[1,0,0] neg_hi:[1,0,0]
	v_pk_fma_f32 v[242:243], v[208:209], v[16:17], v[242:243] neg_lo:[1,0,0] neg_hi:[1,0,0]
	v_pk_fma_f32 v[242:243], v[210:211], v[18:19], v[242:243] neg_lo:[1,0,0] neg_hi:[1,0,0]
	v_pk_fma_f32 v[242:243], v[212:213], v[20:21], v[242:243] neg_lo:[1,0,0] neg_hi:[1,0,0]
	v_pk_fma_f32 v[242:243], v[214:215], v[22:23], v[242:243] neg_lo:[1,0,0] neg_hi:[1,0,0]
	v_pk_fma_f32 v[242:243], v[216:217], v[24:25], v[242:243] neg_lo:[1,0,0] neg_hi:[1,0,0]
	v_pk_fma_f32 v[242:243], v[218:219], v[26:27], v[242:243] neg_lo:[1,0,0] neg_hi:[1,0,0]
	v_pk_fma_f32 v[242:243], v[220:221], v[28:29], v[242:243] neg_lo:[1,0,0] neg_hi:[1,0,0]
	v_pk_fma_f32 v[242:243], v[222:223], v[30:31], v[242:243] neg_lo:[1,0,0] neg_hi:[1,0,0]
	v_pk_fma_f32 v[242:243], v[224:225], v[32:33], v[242:243] neg_lo:[1,0,0] neg_hi:[1,0,0]
	v_cndmask_b32_e64 v240, 0, 1.0, vcc
	v_fma_f32 v242, -v226, v34, v242
	v_add_f32_e32 v35, v242, v243
	v_cmp_eq_u32_e32 vcc, 25, v95
	ds_read_b128 v[204:207], v11 offset:6400
	ds_read_b128 v[208:211], v11 offset:6416
	ds_read_b128 v[212:215], v11 offset:6432
	ds_read_b128 v[216:219], v11 offset:6448
	ds_read_b128 v[220:223], v11 offset:6464
	ds_read_b128 v[224:227], v11 offset:6480
	ds_read_b128 v[232:235], v11 offset:6496
	s_waitcnt lgkmcnt(7)
	v_pk_fma_f32 v[242:243], v[172:173], v[12:13], v[240:241] neg_lo:[1,0,0] neg_hi:[1,0,0]
	v_pk_fma_f32 v[242:243], v[174:175], v[14:15], v[242:243] neg_lo:[1,0,0] neg_hi:[1,0,0]
	v_pk_fma_f32 v[242:243], v[176:177], v[16:17], v[242:243] neg_lo:[1,0,0] neg_hi:[1,0,0]
	v_pk_fma_f32 v[242:243], v[178:179], v[18:19], v[242:243] neg_lo:[1,0,0] neg_hi:[1,0,0]
	v_pk_fma_f32 v[242:243], v[180:181], v[20:21], v[242:243] neg_lo:[1,0,0] neg_hi:[1,0,0]
	v_pk_fma_f32 v[242:243], v[182:183], v[22:23], v[242:243] neg_lo:[1,0,0] neg_hi:[1,0,0]
	v_pk_fma_f32 v[242:243], v[184:185], v[24:25], v[242:243] neg_lo:[1,0,0] neg_hi:[1,0,0]
	v_pk_fma_f32 v[242:243], v[186:187], v[26:27], v[242:243] neg_lo:[1,0,0] neg_hi:[1,0,0]
	v_pk_fma_f32 v[242:243], v[188:189], v[28:29], v[242:243] neg_lo:[1,0,0] neg_hi:[1,0,0]
	v_pk_fma_f32 v[242:243], v[190:191], v[30:31], v[242:243] neg_lo:[1,0,0] neg_hi:[1,0,0]
	v_pk_fma_f32 v[242:243], v[192:193], v[32:33], v[242:243] neg_lo:[1,0,0] neg_hi:[1,0,0]
	v_pk_fma_f32 v[242:243], v[194:195], v[34:35], v[242:243] neg_lo:[1,0,0] neg_hi:[1,0,0]
	v_cndmask_b32_e64 v248, 0, 1.0, vcc
	v_add_f32_e32 v36, v242, v243
	v_cmp_eq_u32_e32 vcc, 26, v95
	ds_read_b128 v[172:175], v11 offset:6656
	ds_read_b128 v[176:179], v11 offset:6672
	ds_read_b128 v[180:183], v11 offset:6688
	ds_read_b128 v[184:187], v11 offset:6704
	ds_read_b128 v[188:191], v11 offset:6720
	ds_read_b128 v[192:195], v11 offset:6736
	ds_read_b128 v[196:199], v11 offset:6752
	s_waitcnt lgkmcnt(7)
	v_pk_fma_f32 v[242:243], v[204:205], v[12:13], v[248:249] neg_lo:[1,0,0] neg_hi:[1,0,0]
	v_pk_fma_f32 v[242:243], v[206:207], v[14:15], v[242:243] neg_lo:[1,0,0] neg_hi:[1,0,0]
	v_pk_fma_f32 v[242:243], v[208:209], v[16:17], v[242:243] neg_lo:[1,0,0] neg_hi:[1,0,0]
	v_pk_fma_f32 v[242:243], v[210:211], v[18:19], v[242:243] neg_lo:[1,0,0] neg_hi:[1,0,0]
	v_pk_fma_f32 v[242:243], v[212:213], v[20:21], v[242:243] neg_lo:[1,0,0] neg_hi:[1,0,0]
	v_pk_fma_f32 v[242:243], v[214:215], v[22:23], v[242:243] neg_lo:[1,0,0] neg_hi:[1,0,0]
	v_pk_fma_f32 v[242:243], v[216:217], v[24:25], v[242:243] neg_lo:[1,0,0] neg_hi:[1,0,0]
	v_pk_fma_f32 v[242:243], v[218:219], v[26:27], v[242:243] neg_lo:[1,0,0] neg_hi:[1,0,0]
	v_pk_fma_f32 v[242:243], v[220:221], v[28:29], v[242:243] neg_lo:[1,0,0] neg_hi:[1,0,0]
	v_pk_fma_f32 v[242:243], v[222:223], v[30:31], v[242:243] neg_lo:[1,0,0] neg_hi:[1,0,0]
	v_pk_fma_f32 v[242:243], v[224:225], v[32:33], v[242:243] neg_lo:[1,0,0] neg_hi:[1,0,0]
	v_pk_fma_f32 v[242:243], v[226:227], v[34:35], v[242:243] neg_lo:[1,0,0] neg_hi:[1,0,0]
	v_cndmask_b32_e64 v240, 0, 1.0, vcc
	v_fma_f32 v242, -v232, v36, v242
	v_add_f32_e32 v37, v242, v243
	v_cmp_eq_u32_e32 vcc, 27, v95
	ds_read_b128 v[204:207], v11 offset:6912
	ds_read_b128 v[208:211], v11 offset:6928
	ds_read_b128 v[212:215], v11 offset:6944
	ds_read_b128 v[216:219], v11 offset:6960
	ds_read_b128 v[220:223], v11 offset:6976
	ds_read_b128 v[224:227], v11 offset:6992
	ds_read_b128 v[232:235], v11 offset:7008
	s_waitcnt lgkmcnt(7)
	v_pk_fma_f32 v[242:243], v[172:173], v[12:13], v[240:241] neg_lo:[1,0,0] neg_hi:[1,0,0]
	v_pk_fma_f32 v[242:243], v[174:175], v[14:15], v[242:243] neg_lo:[1,0,0] neg_hi:[1,0,0]
	v_pk_fma_f32 v[242:243], v[176:177], v[16:17], v[242:243] neg_lo:[1,0,0] neg_hi:[1,0,0]
	v_pk_fma_f32 v[242:243], v[178:179], v[18:19], v[242:243] neg_lo:[1,0,0] neg_hi:[1,0,0]
	v_pk_fma_f32 v[242:243], v[180:181], v[20:21], v[242:243] neg_lo:[1,0,0] neg_hi:[1,0,0]
	v_pk_fma_f32 v[242:243], v[182:183], v[22:23], v[242:243] neg_lo:[1,0,0] neg_hi:[1,0,0]
	v_pk_fma_f32 v[242:243], v[184:185], v[24:25], v[242:243] neg_lo:[1,0,0] neg_hi:[1,0,0]
	v_pk_fma_f32 v[242:243], v[186:187], v[26:27], v[242:243] neg_lo:[1,0,0] neg_hi:[1,0,0]
	v_pk_fma_f32 v[242:243], v[188:189], v[28:29], v[242:243] neg_lo:[1,0,0] neg_hi:[1,0,0]
	v_pk_fma_f32 v[242:243], v[190:191], v[30:31], v[242:243] neg_lo:[1,0,0] neg_hi:[1,0,0]
	v_pk_fma_f32 v[242:243], v[192:193], v[32:33], v[242:243] neg_lo:[1,0,0] neg_hi:[1,0,0]
	v_pk_fma_f32 v[242:243], v[194:195], v[34:35], v[242:243] neg_lo:[1,0,0] neg_hi:[1,0,0]
	v_pk_fma_f32 v[242:243], v[196:197], v[36:37], v[242:243] neg_lo:[1,0,0] neg_hi:[1,0,0]
	v_cndmask_b32_e64 v248, 0, 1.0, vcc
	v_add_f32_e32 v38, v242, v243
	v_cmp_eq_u32_e32 vcc, 28, v95
	ds_read_b128 v[172:175], v11 offset:7168
	ds_read_b128 v[176:179], v11 offset:7184
	ds_read_b128 v[180:183], v11 offset:7200
	ds_read_b128 v[184:187], v11 offset:7216
	ds_read_b128 v[188:191], v11 offset:7232
	ds_read_b128 v[192:195], v11 offset:7248
	ds_read_b128 v[196:199], v11 offset:7264
	s_waitcnt lgkmcnt(7)
	v_pk_fma_f32 v[242:243], v[204:205], v[12:13], v[248:249] neg_lo:[1,0,0] neg_hi:[1,0,0]
	v_pk_fma_f32 v[242:243], v[206:207], v[14:15], v[242:243] neg_lo:[1,0,0] neg_hi:[1,0,0]
	v_pk_fma_f32 v[242:243], v[208:209], v[16:17], v[242:243] neg_lo:[1,0,0] neg_hi:[1,0,0]
	v_pk_fma_f32 v[242:243], v[210:211], v[18:19], v[242:243] neg_lo:[1,0,0] neg_hi:[1,0,0]
	v_pk_fma_f32 v[242:243], v[212:213], v[20:21], v[242:243] neg_lo:[1,0,0] neg_hi:[1,0,0]
	v_pk_fma_f32 v[242:243], v[214:215], v[22:23], v[242:243] neg_lo:[1,0,0] neg_hi:[1,0,0]
	v_pk_fma_f32 v[242:243], v[216:217], v[24:25], v[242:243] neg_lo:[1,0,0] neg_hi:[1,0,0]
	v_pk_fma_f32 v[242:243], v[218:219], v[26:27], v[242:243] neg_lo:[1,0,0] neg_hi:[1,0,0]
	v_pk_fma_f32 v[242:243], v[220:221], v[28:29], v[242:243] neg_lo:[1,0,0] neg_hi:[1,0,0]
	v_pk_fma_f32 v[242:243], v[222:223], v[30:31], v[242:243] neg_lo:[1,0,0] neg_hi:[1,0,0]
	v_pk_fma_f32 v[242:243], v[224:225], v[32:33], v[242:243] neg_lo:[1,0,0] neg_hi:[1,0,0]
	v_pk_fma_f32 v[242:243], v[226:227], v[34:35], v[242:243] neg_lo:[1,0,0] neg_hi:[1,0,0]
	v_pk_fma_f32 v[242:243], v[232:233], v[36:37], v[242:243] neg_lo:[1,0,0] neg_hi:[1,0,0]
	v_cndmask_b32_e64 v240, 0, 1.0, vcc
	v_fma_f32 v242, -v234, v38, v242
	v_add_f32_e32 v39, v242, v243
	v_cmp_eq_u32_e32 vcc, 29, v95
	ds_read_b128 v[204:207], v11 offset:7424
	ds_read_b128 v[208:211], v11 offset:7440
	ds_read_b128 v[212:215], v11 offset:7456
	ds_read_b128 v[216:219], v11 offset:7472
	ds_read_b128 v[220:223], v11 offset:7488
	ds_read_b128 v[224:227], v11 offset:7504
	ds_read_b128 v[232:235], v11 offset:7520
	ds_read_b128 v[236:239], v11 offset:7536
	s_waitcnt lgkmcnt(8)
	v_pk_fma_f32 v[242:243], v[172:173], v[12:13], v[240:241] neg_lo:[1,0,0] neg_hi:[1,0,0]
	v_pk_fma_f32 v[242:243], v[174:175], v[14:15], v[242:243] neg_lo:[1,0,0] neg_hi:[1,0,0]
	v_pk_fma_f32 v[242:243], v[176:177], v[16:17], v[242:243] neg_lo:[1,0,0] neg_hi:[1,0,0]
	v_pk_fma_f32 v[242:243], v[178:179], v[18:19], v[242:243] neg_lo:[1,0,0] neg_hi:[1,0,0]
	v_pk_fma_f32 v[242:243], v[180:181], v[20:21], v[242:243] neg_lo:[1,0,0] neg_hi:[1,0,0]
	v_pk_fma_f32 v[242:243], v[182:183], v[22:23], v[242:243] neg_lo:[1,0,0] neg_hi:[1,0,0]
	v_pk_fma_f32 v[242:243], v[184:185], v[24:25], v[242:243] neg_lo:[1,0,0] neg_hi:[1,0,0]
	v_pk_fma_f32 v[242:243], v[186:187], v[26:27], v[242:243] neg_lo:[1,0,0] neg_hi:[1,0,0]
	v_pk_fma_f32 v[242:243], v[188:189], v[28:29], v[242:243] neg_lo:[1,0,0] neg_hi:[1,0,0]
	v_pk_fma_f32 v[242:243], v[190:191], v[30:31], v[242:243] neg_lo:[1,0,0] neg_hi:[1,0,0]
	v_pk_fma_f32 v[242:243], v[192:193], v[32:33], v[242:243] neg_lo:[1,0,0] neg_hi:[1,0,0]
	v_pk_fma_f32 v[242:243], v[194:195], v[34:35], v[242:243] neg_lo:[1,0,0] neg_hi:[1,0,0]
	v_pk_fma_f32 v[242:243], v[196:197], v[36:37], v[242:243] neg_lo:[1,0,0] neg_hi:[1,0,0]
	v_pk_fma_f32 v[242:243], v[198:199], v[38:39], v[242:243] neg_lo:[1,0,0] neg_hi:[1,0,0]
	v_cndmask_b32_e64 v248, 0, 1.0, vcc
	v_add_f32_e32 v40, v242, v243
	v_cmp_eq_u32_e32 vcc, 30, v95
	ds_read_b128 v[172:175], v11 offset:7680
	ds_read_b128 v[176:179], v11 offset:7696
	ds_read_b128 v[180:183], v11 offset:7712
	ds_read_b128 v[184:187], v11 offset:7728
	ds_read_b128 v[188:191], v11 offset:7744
	ds_read_b128 v[192:195], v11 offset:7760
	ds_read_b128 v[196:199], v11 offset:7776
	ds_read_b128 v[200:203], v11 offset:7792
	s_waitcnt lgkmcnt(8)
	v_pk_fma_f32 v[242:243], v[204:205], v[12:13], v[248:249] neg_lo:[1,0,0] neg_hi:[1,0,0]
	v_pk_fma_f32 v[242:243], v[206:207], v[14:15], v[242:243] neg_lo:[1,0,0] neg_hi:[1,0,0]
	v_pk_fma_f32 v[242:243], v[208:209], v[16:17], v[242:243] neg_lo:[1,0,0] neg_hi:[1,0,0]
	v_pk_fma_f32 v[242:243], v[210:211], v[18:19], v[242:243] neg_lo:[1,0,0] neg_hi:[1,0,0]
	v_pk_fma_f32 v[242:243], v[212:213], v[20:21], v[242:243] neg_lo:[1,0,0] neg_hi:[1,0,0]
	v_pk_fma_f32 v[242:243], v[214:215], v[22:23], v[242:243] neg_lo:[1,0,0] neg_hi:[1,0,0]
	v_pk_fma_f32 v[242:243], v[216:217], v[24:25], v[242:243] neg_lo:[1,0,0] neg_hi:[1,0,0]
	v_pk_fma_f32 v[242:243], v[218:219], v[26:27], v[242:243] neg_lo:[1,0,0] neg_hi:[1,0,0]
	v_pk_fma_f32 v[242:243], v[220:221], v[28:29], v[242:243] neg_lo:[1,0,0] neg_hi:[1,0,0]
	v_pk_fma_f32 v[242:243], v[222:223], v[30:31], v[242:243] neg_lo:[1,0,0] neg_hi:[1,0,0]
	v_pk_fma_f32 v[242:243], v[224:225], v[32:33], v[242:243] neg_lo:[1,0,0] neg_hi:[1,0,0]
	v_pk_fma_f32 v[242:243], v[226:227], v[34:35], v[242:243] neg_lo:[1,0,0] neg_hi:[1,0,0]
	v_pk_fma_f32 v[242:243], v[232:233], v[36:37], v[242:243] neg_lo:[1,0,0] neg_hi:[1,0,0]
	v_pk_fma_f32 v[242:243], v[234:235], v[38:39], v[242:243] neg_lo:[1,0,0] neg_hi:[1,0,0]
	v_cndmask_b32_e64 v240, 0, 1.0, vcc
	v_fma_f32 v242, -v236, v40, v242
	v_add_f32_e32 v41, v242, v243
	v_cmp_eq_u32_e32 vcc, 31, v95
	ds_read_b128 v[204:207], v11 offset:7936
	ds_read_b128 v[208:211], v11 offset:7952
	ds_read_b128 v[212:215], v11 offset:7968
	ds_read_b128 v[216:219], v11 offset:7984
	ds_read_b128 v[220:223], v11 offset:8000
	ds_read_b128 v[224:227], v11 offset:8016
	ds_read_b128 v[232:235], v11 offset:8032
	ds_read_b128 v[236:239], v11 offset:8048
	s_waitcnt lgkmcnt(8)
	v_pk_fma_f32 v[242:243], v[172:173], v[12:13], v[240:241] neg_lo:[1,0,0] neg_hi:[1,0,0]
	v_pk_fma_f32 v[242:243], v[174:175], v[14:15], v[242:243] neg_lo:[1,0,0] neg_hi:[1,0,0]
	v_pk_fma_f32 v[242:243], v[176:177], v[16:17], v[242:243] neg_lo:[1,0,0] neg_hi:[1,0,0]
	v_pk_fma_f32 v[242:243], v[178:179], v[18:19], v[242:243] neg_lo:[1,0,0] neg_hi:[1,0,0]
	v_pk_fma_f32 v[242:243], v[180:181], v[20:21], v[242:243] neg_lo:[1,0,0] neg_hi:[1,0,0]
	v_pk_fma_f32 v[242:243], v[182:183], v[22:23], v[242:243] neg_lo:[1,0,0] neg_hi:[1,0,0]
	v_pk_fma_f32 v[242:243], v[184:185], v[24:25], v[242:243] neg_lo:[1,0,0] neg_hi:[1,0,0]
	v_pk_fma_f32 v[242:243], v[186:187], v[26:27], v[242:243] neg_lo:[1,0,0] neg_hi:[1,0,0]
	v_pk_fma_f32 v[242:243], v[188:189], v[28:29], v[242:243] neg_lo:[1,0,0] neg_hi:[1,0,0]
	v_pk_fma_f32 v[242:243], v[190:191], v[30:31], v[242:243] neg_lo:[1,0,0] neg_hi:[1,0,0]
	v_pk_fma_f32 v[242:243], v[192:193], v[32:33], v[242:243] neg_lo:[1,0,0] neg_hi:[1,0,0]
	v_pk_fma_f32 v[242:243], v[194:195], v[34:35], v[242:243] neg_lo:[1,0,0] neg_hi:[1,0,0]
	v_pk_fma_f32 v[242:243], v[196:197], v[36:37], v[242:243] neg_lo:[1,0,0] neg_hi:[1,0,0]
	v_pk_fma_f32 v[242:243], v[198:199], v[38:39], v[242:243] neg_lo:[1,0,0] neg_hi:[1,0,0]
	v_pk_fma_f32 v[242:243], v[200:201], v[40:41], v[242:243] neg_lo:[1,0,0] neg_hi:[1,0,0]
	v_cndmask_b32_e64 v248, 0, 1.0, vcc
	v_add_f32_e32 v42, v242, v243
	s_waitcnt lgkmcnt(0)
	v_pk_fma_f32 v[242:243], v[204:205], v[12:13], v[248:249] neg_lo:[1,0,0] neg_hi:[1,0,0]
	v_pk_fma_f32 v[242:243], v[206:207], v[14:15], v[242:243] neg_lo:[1,0,0] neg_hi:[1,0,0]
	v_pk_fma_f32 v[242:243], v[208:209], v[16:17], v[242:243] neg_lo:[1,0,0] neg_hi:[1,0,0]
	v_pk_fma_f32 v[242:243], v[210:211], v[18:19], v[242:243] neg_lo:[1,0,0] neg_hi:[1,0,0]
	v_pk_fma_f32 v[242:243], v[212:213], v[20:21], v[242:243] neg_lo:[1,0,0] neg_hi:[1,0,0]
	v_pk_fma_f32 v[242:243], v[214:215], v[22:23], v[242:243] neg_lo:[1,0,0] neg_hi:[1,0,0]
	v_pk_fma_f32 v[242:243], v[216:217], v[24:25], v[242:243] neg_lo:[1,0,0] neg_hi:[1,0,0]
	v_pk_fma_f32 v[242:243], v[218:219], v[26:27], v[242:243] neg_lo:[1,0,0] neg_hi:[1,0,0]
	v_pk_fma_f32 v[242:243], v[220:221], v[28:29], v[242:243] neg_lo:[1,0,0] neg_hi:[1,0,0]
	v_pk_fma_f32 v[242:243], v[222:223], v[30:31], v[242:243] neg_lo:[1,0,0] neg_hi:[1,0,0]
	v_pk_fma_f32 v[242:243], v[224:225], v[32:33], v[242:243] neg_lo:[1,0,0] neg_hi:[1,0,0]
	v_pk_fma_f32 v[242:243], v[226:227], v[34:35], v[242:243] neg_lo:[1,0,0] neg_hi:[1,0,0]
	v_pk_fma_f32 v[242:243], v[232:233], v[36:37], v[242:243] neg_lo:[1,0,0] neg_hi:[1,0,0]
	v_pk_fma_f32 v[242:243], v[234:235], v[38:39], v[242:243] neg_lo:[1,0,0] neg_hi:[1,0,0]
	v_pk_fma_f32 v[242:243], v[236:237], v[40:41], v[242:243] neg_lo:[1,0,0] neg_hi:[1,0,0]
	v_fma_f32 v242, -v238, v42, v242
	v_add_f32_e32 v43, v242, v243
	v_cvt_pk_bf16_f32 v244, v12, v12
	ds_write_b16 v0, v244
	v_cvt_pk_bf16_f32 v245, v13, v13
	ds_write_b16 v0, v245 offset:80
	v_cvt_pk_bf16_f32 v244, v14, v14
	ds_write_b16 v0, v244 offset:160
	v_cvt_pk_bf16_f32 v245, v15, v15
	ds_write_b16 v0, v245 offset:240
	v_cvt_pk_bf16_f32 v244, v16, v16
	ds_write_b16 v0, v244 offset:320
	v_cvt_pk_bf16_f32 v245, v17, v17
	ds_write_b16 v0, v245 offset:400
	v_cvt_pk_bf16_f32 v244, v18, v18
	ds_write_b16 v0, v244 offset:480
	v_cvt_pk_bf16_f32 v245, v19, v19
	ds_write_b16 v0, v245 offset:560
	v_cvt_pk_bf16_f32 v244, v20, v20
	ds_write_b16 v0, v244 offset:640
	v_cvt_pk_bf16_f32 v245, v21, v21
	ds_write_b16 v0, v245 offset:720
	v_cvt_pk_bf16_f32 v244, v22, v22
	ds_write_b16 v0, v244 offset:800
	v_cvt_pk_bf16_f32 v245, v23, v23
	ds_write_b16 v0, v245 offset:880
	v_cvt_pk_bf16_f32 v244, v24, v24
	ds_write_b16 v0, v244 offset:960
	v_cvt_pk_bf16_f32 v245, v25, v25
	ds_write_b16 v0, v245 offset:1040
	v_cvt_pk_bf16_f32 v244, v26, v26
	ds_write_b16 v0, v244 offset:1120
	v_cvt_pk_bf16_f32 v245, v27, v27
	ds_write_b16 v0, v245 offset:1200
	v_cvt_pk_bf16_f32 v244, v28, v28
	ds_write_b16 v0, v244 offset:1280
	v_cvt_pk_bf16_f32 v245, v29, v29
	ds_write_b16 v0, v245 offset:1360
	v_cvt_pk_bf16_f32 v244, v30, v30
	ds_write_b16 v0, v244 offset:1440
	v_cvt_pk_bf16_f32 v245, v31, v31
	ds_write_b16 v0, v245 offset:1520
	v_cvt_pk_bf16_f32 v244, v32, v32
	ds_write_b16 v0, v244 offset:1600
	v_cvt_pk_bf16_f32 v245, v33, v33
	ds_write_b16 v0, v245 offset:1680
	v_cvt_pk_bf16_f32 v244, v34, v34
	ds_write_b16 v0, v244 offset:1760
	v_cvt_pk_bf16_f32 v245, v35, v35
	ds_write_b16 v0, v245 offset:1840
	v_cvt_pk_bf16_f32 v244, v36, v36
	ds_write_b16 v0, v244 offset:1920
	v_cvt_pk_bf16_f32 v245, v37, v37
	ds_write_b16 v0, v245 offset:2000
	v_cvt_pk_bf16_f32 v244, v38, v38
	ds_write_b16 v0, v244 offset:2080
	v_cvt_pk_bf16_f32 v245, v39, v39
	ds_write_b16 v0, v245 offset:2160
	v_cvt_pk_bf16_f32 v244, v40, v40
	ds_write_b16 v0, v244 offset:2240
	v_cvt_pk_bf16_f32 v245, v41, v41
	ds_write_b16 v0, v245 offset:2320
	v_cvt_pk_bf16_f32 v244, v42, v42
	ds_write_b16 v0, v244 offset:2400
	v_cvt_pk_bf16_f32 v245, v43, v43
	ds_write_b16 v0, v245 offset:2480
	s_setprio 0
